# out-proj L1: bf16 residual tile fetched at phase start and used as the accumulators initial value (epilogue without residual loads); on top of the previous edits
# speedup vs baseline: 1.0504x; 1.0019x over previous
.LBB0_1514:
	s_andn2_b64 vcc, exec, s[6:7]
	s_cbranch_vccnz .LBB0_1552
	v_ashrrev_i32_e32 v1, 31, v8
	v_lshrrev_b32_e32 v1, 26, v1
	v_add_u32_e32 v1, v8, v1
	v_ashrrev_i32_e32 v9, 6, v1
	v_bfe_i32 v1, v8, 27, 1
	v_lshlrev_b32_e32 v0, 4, v8
	v_lshrrev_b32_e32 v1, 22, v1
	v_add_u32_e32 v1, v0, v1
	v_and_b32_e32 v1, 0xfffffc00, v1
	v_sub_u32_e32 v1, v0, v1
	v_lshrrev_b32_e32 v2, 4, v1
	v_bitop3_b32 v1, v2, v1, 32 bitop3:0x6c
	v_ashrrev_i32_e32 v3, 31, v1
	v_lshrrev_b32_e32 v3, 26, v3
	v_add_u32_e32 v3, v1, v3
	v_lshlrev_b32_e32 v2, 3, v9
	v_ashrrev_i32_e32 v11, 6, v3
	v_and_b32_e32 v3, 0xc0, v3
	s_waitcnt lgkmcnt(0)
	s_add_u32 s37, s4, 0x4300000
	v_and_b32_e32 v2, -16, v2
	v_sub_u32_e32 v1, v1, v3
	v_mov_b32_e32 v3, 1
	s_addc_u32 s38, s5, 0
	v_add_u32_e32 v2, v11, v2
	v_lshlrev_b32_e32 v4, 5, v9
	v_ashrrev_i16_sdwa v1, v3, sext(v1) dst_sel:DWORD dst_unused:UNUSED_PAD src0_sel:DWORD src1_sel:BYTE_0
	s_add_u32 s39, s4, 0x880000
	v_and_b32_e32 v10, 32, v4
	v_bfe_i32 v12, v1, 0, 16
	v_lshlrev_b32_e32 v4, 1, v2
	v_lshrrev_b32_e32 v5, 2, v2
	v_and_b32_e32 v6, 3, v11
	s_mov_b32 s6, 0x1fffe0
	s_movk_i32 s4, 0xf00
	v_add_u32_e32 v1, v10, v12
	v_and_b32_e32 v4, 24, v4
	v_and_b32_e32 v5, 4, v5
	v_and_or_b32 v6, v2, s6, v6
	v_mul_lo_u32 v2, v2, s4
	v_or3_b32 v4, v6, v5, v4
	v_add_lshl_u32 v128, v1, v2, 1
	v_lshlrev_b32_e32 v1, 1, v1
	v_add_u32_e32 v0, 0x2000, v0
	v_lshl_add_u32 v130, v4, 11, v1
	v_ashrrev_i32_e32 v1, 31, v0
	v_lshrrev_b32_e32 v1, 22, v1
	v_add_u32_e32 v1, v0, v1
	v_ashrrev_i32_e32 v13, 10, v1
	v_mul_i32_i24_e32 v1, 0x400, v13
	v_sub_u32_e32 v0, v0, v1
	v_lshrrev_b32_e32 v1, 4, v0
	v_bitop3_b32 v0, v1, v0, 32 bitop3:0x6c
	v_ashrrev_i32_e32 v2, 31, v0
	v_lshrrev_b32_e32 v2, 26, v2
	v_lshlrev_b32_e32 v1, 3, v13
	v_add_u32_e32 v2, v0, v2
	v_and_b32_e32 v1, -16, v1
	v_ashrrev_i32_e32 v15, 6, v2
	v_lshlrev_b32_e32 v4, 5, v13
	v_add_u32_e32 v1, v15, v1
	v_and_b32_e32 v14, 32, v4
	v_and_b32_e32 v4, 3, v15
	s_addc_u32 s40, s5, 0
	v_and_b32_e32 v2, 0xc0, v2
	v_and_or_b32 v4, v1, s6, v4
	s_ashr_i32 s6, s16, 6
	s_ashr_i32 s31, s30, 31
	s_ashr_i32 s5, s16, 8
	v_sub_u32_e32 v0, v0, v2
	s_lshl_b32 s41, s6, 10
	s_lshl_b64 s[8:9], s[30:31], 19
	v_ashrrev_i16_sdwa v0, v3, sext(v0) dst_sel:DWORD dst_unused:UNUSED_PAD src0_sel:DWORD src1_sel:BYTE_0
	s_add_u32 s10, s39, s8
	s_waitcnt vmcnt(0)
	v_bfe_i32 v16, v0, 0, 16
	v_lshlrev_b32_e32 v2, 1, v1
	v_lshrrev_b32_e32 v3, 2, v1
	s_addc_u32 s11, s40, s9
	s_add_i32 s31, s41, 0
	v_add_u32_e32 v0, v14, v16
	v_and_b32_e32 v2, 24, v2
	v_and_b32_e32 v3, 4, v3
	v_mul_lo_u32 v1, v1, s4
	s_add_i32 m0, s31, 0x10000
	v_or3_b32 v2, v4, v3, v2
	v_add_lshl_u32 v132, v0, v1, 1
	v_lshlrev_b32_e32 v0, 1, v0
	s_load_dwordx2 s[96:97], s[0:1], 0x130
	v_bfe_u32 v236, v154, 4, 2
	v_lshrrev_b32_e32 v237, 8, v154
	v_bfe_u32 v238, v154, 6, 2
	v_and_b32_e32 v239, 15, v154
	v_lshl_add_u32 v239, v237, 6, v239
	v_lshl_add_u32 v239, s56, 8, v239
	v_lshlrev_b32_e32 v238, 5, v238
	v_lshl_add_u32 v238, v236, 3, v238
	v_lshl_add_u32 v238, s30, 8, v238
	v_lshlrev_b32_e32 v239, 11, v239
	v_lshl_add_u32 v244, v238, 1, v239
	v_add_u32_e32 v245, 0x8000, v244
	v_add_u32_e32 v246, 0x10000, v244
	v_add_u32_e32 v247, 0x18000, v244
	v_add_u32_e32 v248, 0x40000, v244
	v_add_u32_e32 v249, 0x48000, v244
	v_add_u32_e32 v250, 0x50000, v244
	v_add_u32_e32 v251, 0x58000, v244
	s_waitcnt lgkmcnt(0)
	s_add_u32 s96, s96, 0x2000000
	s_addc_u32 s97, s97, 0
	global_load_dwordx4 v[160:163], v244, s[96:97]
	global_load_dwordx4 v[164:167], v244, s[96:97] offset:256
	global_load_dwordx4 v[168:171], v245, s[96:97]
	global_load_dwordx4 v[172:175], v245, s[96:97] offset:256
	global_load_dwordx4 v[176:179], v246, s[96:97]
	global_load_dwordx4 v[180:183], v246, s[96:97] offset:256
	global_load_dwordx4 v[184:187], v247, s[96:97]
	global_load_dwordx4 v[188:191], v247, s[96:97] offset:256
	global_load_dwordx4 v[192:195], v248, s[96:97]
	global_load_dwordx4 v[196:199], v248, s[96:97] offset:256
	global_load_dwordx4 v[200:203], v249, s[96:97]
	global_load_dwordx4 v[204:207], v249, s[96:97] offset:256
	global_load_dwordx4 v[208:211], v250, s[96:97]
	global_load_dwordx4 v[212:215], v250, s[96:97] offset:256
	global_load_dwordx4 v[216:219], v251, s[96:97]
	global_load_dwordx4 v[220:223], v251, s[96:97] offset:256
	s_mov_b32 s98, 1
	global_load_lds_dwordx4 v130, s[10:11]
	s_add_i32 m0, s31, 0x12000
	v_lshl_add_u32 v134, v2, 11, v0
	s_add_u32 s8, s10, 0x40000
	global_load_lds_dwordx4 v134, s[10:11]
	s_addc_u32 s9, s11, 0
	s_add_i32 m0, s31, 0x14000
	s_mul_i32 s12, s56, 0x1e0000
	global_load_lds_dwordx4 v130, s[8:9]
	s_add_i32 m0, s31, 0x16000
	s_mul_hi_i32 s7, s56, 0x1e0000
	global_load_lds_dwordx4 v134, s[8:9]
	s_add_u32 s8, s37, s12
	s_addc_u32 s9, s38, s7
	s_add_i32 s42, s31, 0x2000
	s_mov_b32 m0, s31
	s_add_u32 s12, s8, 0xf0000
	global_load_lds_dwordx4 v128, s[8:9]
	s_mov_b32 m0, s42
	s_addc_u32 s13, s9, 0
	s_add_i32 s43, s31, 0x4000
	global_load_lds_dwordx4 v132, s[8:9]
	s_mov_b32 m0, s43
	s_add_i32 s44, s31, 0x6000
	global_load_lds_dwordx4 v128, s[12:13]
	s_mov_b32 m0, s44
	v_mov_b32_e32 v131, 0
	global_load_lds_dwordx4 v132, s[12:13]
	v_mov_b32_e32 v135, v131
	v_mov_b32_e32 v129, v131
	v_mov_b32_e32 v133, v131
	s_cmp_eq_u32 s5, 1
	s_mov_b32 s45, 0
	v_lshl_add_u64 v[6:7], s[10:11], 0, v[130:131]
	v_lshl_add_u64 v[4:5], s[10:11], 0, v[134:135]
	v_lshl_add_u64 v[0:1], s[8:9], 0, v[128:129]
	s_cselect_b64 s[12:13], -1, 0
	s_cmp_lg_u32 s5, 1
	v_lshl_add_u64 v[2:3], s[8:9], 0, v[132:133]
	s_cbranch_scc1 .LBB0_1517
	s_barrier

.LBB0_1528:
	s_ashr_i32 s19, s18, 31
	s_lshl_b64 s[28:29], s[18:19], 19
	s_add_u32 s28, s39, s28
	s_addc_u32 s29, s40, s29
	s_and_b64 s[6:7], s[6:7], exec
	s_cselect_b32 s19, s29, s11
	s_cselect_b32 s57, s28, s10
	s_add_u32 s58, s10, 0x100
	s_addc_u32 s59, s11, 0
	s_mov_b32 s60, -2
	s_waitcnt lgkmcnt(0)
	s_cmp_eq_u32 s98, 1
	s_cbranch_scc1 .Lro1_unpack
	s_load_dwordx2 s[96:97], s[0:1], 0x130
	v_bfe_u32 v236, v154, 4, 2
	v_lshrrev_b32_e32 v237, 8, v154
	v_bfe_u32 v238, v154, 6, 2
	v_and_b32_e32 v239, 15, v154
	v_lshl_add_u32 v239, v237, 6, v239
	v_lshl_add_u32 v239, s56, 8, v239
	v_lshlrev_b32_e32 v238, 5, v238
	v_lshl_add_u32 v238, v236, 3, v238
	v_lshl_add_u32 v238, s30, 8, v238
	v_lshlrev_b32_e32 v239, 11, v239
	v_lshl_add_u32 v244, v238, 1, v239
	v_add_u32_e32 v245, 0x8000, v244
	v_add_u32_e32 v246, 0x10000, v244
	v_add_u32_e32 v247, 0x18000, v244
	v_add_u32_e32 v248, 0x40000, v244
	v_add_u32_e32 v249, 0x48000, v244
	v_add_u32_e32 v250, 0x50000, v244
	v_add_u32_e32 v251, 0x58000, v244
	s_waitcnt lgkmcnt(0)
	s_add_u32 s96, s96, 0x2000000
	s_addc_u32 s97, s97, 0
	global_load_dwordx4 v[160:163], v244, s[96:97]
	global_load_dwordx4 v[164:167], v244, s[96:97] offset:256
	global_load_dwordx4 v[168:171], v245, s[96:97]
	global_load_dwordx4 v[172:175], v245, s[96:97] offset:256
	global_load_dwordx4 v[176:179], v246, s[96:97]
	global_load_dwordx4 v[180:183], v246, s[96:97] offset:256
	global_load_dwordx4 v[184:187], v247, s[96:97]
	global_load_dwordx4 v[188:191], v247, s[96:97] offset:256
	global_load_dwordx4 v[192:195], v248, s[96:97]
	global_load_dwordx4 v[196:199], v248, s[96:97] offset:256
	global_load_dwordx4 v[200:203], v249, s[96:97]
	global_load_dwordx4 v[204:207], v249, s[96:97] offset:256
	global_load_dwordx4 v[208:211], v250, s[96:97]
	global_load_dwordx4 v[212:215], v250, s[96:97] offset:256
	global_load_dwordx4 v[216:219], v251, s[96:97]
	global_load_dwordx4 v[220:223], v251, s[96:97] offset:256
	s_waitcnt vmcnt(0)
.Lro1_unpack:
	s_mov_b32 s98, 0
	v_lshlrev_b32_e32 v124, 16, v160
	v_and_b32_e32 v125, 0xffff0000, v160
	v_lshlrev_b32_e32 v126, 16, v161
	v_and_b32_e32 v127, 0xffff0000, v161
	v_lshlrev_b32_e32 v120, 16, v162
	v_and_b32_e32 v121, 0xffff0000, v162
	v_lshlrev_b32_e32 v122, 16, v163
	v_and_b32_e32 v123, 0xffff0000, v163
	v_lshlrev_b32_e32 v116, 16, v164
	v_and_b32_e32 v117, 0xffff0000, v164
	v_lshlrev_b32_e32 v118, 16, v165
	v_and_b32_e32 v119, 0xffff0000, v165
	v_lshlrev_b32_e32 v112, 16, v166
	v_and_b32_e32 v113, 0xffff0000, v166
	v_lshlrev_b32_e32 v114, 16, v167
	v_and_b32_e32 v115, 0xffff0000, v167
	v_lshlrev_b32_e32 v108, 16, v168
	v_and_b32_e32 v109, 0xffff0000, v168
	v_lshlrev_b32_e32 v110, 16, v169
	v_and_b32_e32 v111, 0xffff0000, v169
	v_lshlrev_b32_e32 v104, 16, v170
	v_and_b32_e32 v105, 0xffff0000, v170
	v_lshlrev_b32_e32 v106, 16, v171
	v_and_b32_e32 v107, 0xffff0000, v171
	v_lshlrev_b32_e32 v100, 16, v172
	v_and_b32_e32 v101, 0xffff0000, v172
	v_lshlrev_b32_e32 v102, 16, v173
	v_and_b32_e32 v103, 0xffff0000, v173
	v_lshlrev_b32_e32 v96, 16, v174
	v_and_b32_e32 v97, 0xffff0000, v174
	v_lshlrev_b32_e32 v98, 16, v175
	v_and_b32_e32 v99, 0xffff0000, v175
	v_lshlrev_b32_e32 v92, 16, v176
	v_and_b32_e32 v93, 0xffff0000, v176
	v_lshlrev_b32_e32 v94, 16, v177
	v_and_b32_e32 v95, 0xffff0000, v177
	v_lshlrev_b32_e32 v88, 16, v178
	v_and_b32_e32 v89, 0xffff0000, v178
	v_lshlrev_b32_e32 v90, 16, v179
	v_and_b32_e32 v91, 0xffff0000, v179
	v_lshlrev_b32_e32 v84, 16, v180
	v_and_b32_e32 v85, 0xffff0000, v180
	v_lshlrev_b32_e32 v86, 16, v181
	v_and_b32_e32 v87, 0xffff0000, v181
	v_lshlrev_b32_e32 v80, 16, v182
	v_and_b32_e32 v81, 0xffff0000, v182
	v_lshlrev_b32_e32 v82, 16, v183
	v_and_b32_e32 v83, 0xffff0000, v183
	v_lshlrev_b32_e32 v76, 16, v184
	v_and_b32_e32 v77, 0xffff0000, v184
	v_lshlrev_b32_e32 v78, 16, v185
	v_and_b32_e32 v79, 0xffff0000, v185
	v_lshlrev_b32_e32 v72, 16, v186
	v_and_b32_e32 v73, 0xffff0000, v186
	v_lshlrev_b32_e32 v74, 16, v187
	v_and_b32_e32 v75, 0xffff0000, v187
	v_lshlrev_b32_e32 v68, 16, v188
	v_and_b32_e32 v69, 0xffff0000, v188
	v_lshlrev_b32_e32 v70, 16, v189
	v_and_b32_e32 v71, 0xffff0000, v189
	v_lshlrev_b32_e32 v64, 16, v190
	v_and_b32_e32 v65, 0xffff0000, v190
	v_lshlrev_b32_e32 v66, 16, v191
	v_and_b32_e32 v67, 0xffff0000, v191
	v_lshlrev_b32_e32 v60, 16, v192
	v_and_b32_e32 v61, 0xffff0000, v192
	v_lshlrev_b32_e32 v62, 16, v193
	v_and_b32_e32 v63, 0xffff0000, v193
	v_lshlrev_b32_e32 v56, 16, v194
	v_and_b32_e32 v57, 0xffff0000, v194
	v_lshlrev_b32_e32 v58, 16, v195
	v_and_b32_e32 v59, 0xffff0000, v195
	v_lshlrev_b32_e32 v52, 16, v196
	v_and_b32_e32 v53, 0xffff0000, v196
	v_lshlrev_b32_e32 v54, 16, v197
	v_and_b32_e32 v55, 0xffff0000, v197
	v_lshlrev_b32_e32 v48, 16, v198
	v_and_b32_e32 v49, 0xffff0000, v198
	v_lshlrev_b32_e32 v50, 16, v199
	v_and_b32_e32 v51, 0xffff0000, v199
	v_lshlrev_b32_e32 v44, 16, v200
	v_and_b32_e32 v45, 0xffff0000, v200
	v_lshlrev_b32_e32 v46, 16, v201
	v_and_b32_e32 v47, 0xffff0000, v201
	v_lshlrev_b32_e32 v40, 16, v202
	v_and_b32_e32 v41, 0xffff0000, v202
	v_lshlrev_b32_e32 v42, 16, v203
	v_and_b32_e32 v43, 0xffff0000, v203
	v_lshlrev_b32_e32 v36, 16, v204
	v_and_b32_e32 v37, 0xffff0000, v204
	v_lshlrev_b32_e32 v38, 16, v205
	v_and_b32_e32 v39, 0xffff0000, v205
	v_lshlrev_b32_e32 v32, 16, v206
	v_and_b32_e32 v33, 0xffff0000, v206
	v_lshlrev_b32_e32 v34, 16, v207
	v_and_b32_e32 v35, 0xffff0000, v207
	v_lshlrev_b32_e32 v28, 16, v208
	v_and_b32_e32 v29, 0xffff0000, v208
	v_lshlrev_b32_e32 v30, 16, v209
	v_and_b32_e32 v31, 0xffff0000, v209
	v_lshlrev_b32_e32 v24, 16, v210
	v_and_b32_e32 v25, 0xffff0000, v210
	v_lshlrev_b32_e32 v26, 16, v211
	v_and_b32_e32 v27, 0xffff0000, v211
	v_lshlrev_b32_e32 v20, 16, v212
	v_and_b32_e32 v21, 0xffff0000, v212
	v_lshlrev_b32_e32 v22, 16, v213
	v_and_b32_e32 v23, 0xffff0000, v213
	v_lshlrev_b32_e32 v16, 16, v214
	v_and_b32_e32 v17, 0xffff0000, v214
	v_lshlrev_b32_e32 v18, 16, v215
	v_and_b32_e32 v19, 0xffff0000, v215
	v_lshlrev_b32_e32 v12, 16, v216
	v_and_b32_e32 v13, 0xffff0000, v216
	v_lshlrev_b32_e32 v14, 16, v217
	v_and_b32_e32 v15, 0xffff0000, v217
	v_lshlrev_b32_e32 v8, 16, v218
	v_and_b32_e32 v9, 0xffff0000, v218
	v_lshlrev_b32_e32 v10, 16, v219
	v_and_b32_e32 v11, 0xffff0000, v219
	v_lshlrev_b32_e32 v4, 16, v220
	v_and_b32_e32 v5, 0xffff0000, v220
	v_lshlrev_b32_e32 v6, 16, v221
	v_and_b32_e32 v7, 0xffff0000, v221
	v_lshlrev_b32_e32 v0, 16, v222
	v_and_b32_e32 v1, 0xffff0000, v222
	v_lshlrev_b32_e32 v2, 16, v223
	v_and_b32_e32 v3, 0xffff0000, v223

.LBB0_1532:
	v_bfe_u32 v156, v154, 4, 2
	s_lshl_b32 s94, s56, 8
	s_add_i32 s94, s94, s47
	v_and_or_b32 v146, v154, 15, s94
	s_lshl_b32 s94, s30, 8
	s_or_b32 s94, s94, s48
	v_lshl_or_b32 v144, v156, 3, s94
	s_lshl_b32 s94, s30, 2
	s_or_b32 s94, s94, s46
	s_lshl_b32 s94, s94, 2
	s_load_dwordx4 s[8:11], s[0:1], 0x130
	v_lshlrev_b32_e32 v145, 11, v146
	v_lshl_add_u32 v224, v144, 1, v145
	v_lshlrev_b32_e32 v147, 6, v146
	v_add_u32_e32 v225, 0x8000, v224
	v_add_u32_e32 v226, 0x10000, v224
	v_add_u32_e32 v227, 0x18000, v224
	v_add_u32_e32 v228, 0x40000, v224
	v_add_u32_e32 v229, 0x48000, v224
	v_add_u32_e32 v230, 0x50000, v224
	v_add_u32_e32 v231, 0x58000, v224
	s_waitcnt lgkmcnt(0)
	s_add_u32 s8, s8, 0x2000000
	s_addc_u32 s9, s9, 0
	s_add_u32 s10, s10, s94
	s_addc_u32 s11, s11, 0
	s_add_u32 s10, s10, 0xfe00000
	s_addc_u32 s11, s11, 0
	v_mul_f32_e32 v157, v125, v125
	v_mul_f32_e32 v158, v127, v127
	v_mul_f32_e32 v159, v121, v121
	v_mul_f32_e32 v153, v123, v123
	v_fmac_f32_e32 v157, v124, v124
	v_fmac_f32_e32 v158, v126, v126
	v_fmac_f32_e32 v159, v120, v120
	v_fmac_f32_e32 v153, v122, v122
	v_add_f32_e32 v157, v157, v158
	v_add_f32_e32 v157, v159, v157
	v_add_f32_e32 v232, v153, v157
	v_cvt_pk_bf16_f32 v248, v124, v125
	v_cvt_pk_bf16_f32 v249, v126, v127
	v_cvt_pk_bf16_f32 v250, v120, v121
	v_cvt_pk_bf16_f32 v251, v122, v123
	global_store_dwordx4 v224, v[248:251], s[8:9]
	v_mul_f32_e32 v157, v117, v117
	v_mul_f32_e32 v158, v119, v119
	v_mul_f32_e32 v159, v113, v113
	v_mul_f32_e32 v153, v115, v115
	v_fmac_f32_e32 v157, v116, v116
	v_fmac_f32_e32 v158, v118, v118
	v_fmac_f32_e32 v159, v112, v112
	v_fmac_f32_e32 v153, v114, v114
	v_add_f32_e32 v157, v157, v158
	v_add_f32_e32 v157, v159, v157
	v_add_f32_e32 v157, v153, v157
	v_add_f32_e32 v232, v232, v157
	v_cvt_pk_bf16_f32 v252, v116, v117
	v_cvt_pk_bf16_f32 v253, v118, v119
	v_cvt_pk_bf16_f32 v254, v112, v113
	v_cvt_pk_bf16_f32 v255, v114, v115
	global_store_dwordx4 v224, v[252:255], s[8:9] offset:256
	v_mul_f32_e32 v157, v109, v109
	v_mul_f32_e32 v158, v111, v111
	v_mul_f32_e32 v159, v105, v105
	v_mul_f32_e32 v153, v107, v107
	v_fmac_f32_e32 v157, v108, v108
	v_fmac_f32_e32 v158, v110, v110
	v_fmac_f32_e32 v159, v104, v104
	v_fmac_f32_e32 v153, v106, v106
	v_add_f32_e32 v157, v157, v158
	v_add_f32_e32 v157, v159, v157
	v_add_f32_e32 v233, v153, v157
	v_cvt_pk_bf16_f32 v248, v108, v109
	v_cvt_pk_bf16_f32 v249, v110, v111
	v_cvt_pk_bf16_f32 v250, v104, v105
	v_cvt_pk_bf16_f32 v251, v106, v107
	global_store_dwordx4 v225, v[248:251], s[8:9]
	v_mul_f32_e32 v157, v101, v101
	v_mul_f32_e32 v158, v103, v103
	v_mul_f32_e32 v159, v97, v97
	v_mul_f32_e32 v153, v99, v99
	v_fmac_f32_e32 v157, v100, v100
	v_fmac_f32_e32 v158, v102, v102
	v_fmac_f32_e32 v159, v96, v96
	v_fmac_f32_e32 v153, v98, v98
	v_add_f32_e32 v157, v157, v158
	v_add_f32_e32 v157, v159, v157
	v_add_f32_e32 v157, v153, v157
	v_add_f32_e32 v233, v233, v157
	v_cvt_pk_bf16_f32 v252, v100, v101
	v_cvt_pk_bf16_f32 v253, v102, v103
	v_cvt_pk_bf16_f32 v254, v96, v97
	v_cvt_pk_bf16_f32 v255, v98, v99
	global_store_dwordx4 v225, v[252:255], s[8:9] offset:256
	v_mul_f32_e32 v157, v93, v93
	v_mul_f32_e32 v158, v95, v95
	v_mul_f32_e32 v159, v89, v89
	v_mul_f32_e32 v153, v91, v91
	v_fmac_f32_e32 v157, v92, v92
	v_fmac_f32_e32 v158, v94, v94
	v_fmac_f32_e32 v159, v88, v88
	v_fmac_f32_e32 v153, v90, v90
	v_add_f32_e32 v157, v157, v158
	v_add_f32_e32 v157, v159, v157
	v_add_f32_e32 v234, v153, v157
	v_cvt_pk_bf16_f32 v248, v92, v93
	v_cvt_pk_bf16_f32 v249, v94, v95
	v_cvt_pk_bf16_f32 v250, v88, v89
	v_cvt_pk_bf16_f32 v251, v90, v91
	global_store_dwordx4 v226, v[248:251], s[8:9]
	v_mul_f32_e32 v157, v85, v85
	v_mul_f32_e32 v158, v87, v87
	v_mul_f32_e32 v159, v81, v81
	v_mul_f32_e32 v153, v83, v83
	v_fmac_f32_e32 v157, v84, v84
	v_fmac_f32_e32 v158, v86, v86
	v_fmac_f32_e32 v159, v80, v80
	v_fmac_f32_e32 v153, v82, v82
	v_add_f32_e32 v157, v157, v158
	v_add_f32_e32 v157, v159, v157
	v_add_f32_e32 v157, v153, v157
	v_add_f32_e32 v234, v234, v157
	v_cvt_pk_bf16_f32 v252, v84, v85
	v_cvt_pk_bf16_f32 v253, v86, v87
	v_cvt_pk_bf16_f32 v254, v80, v81
	v_cvt_pk_bf16_f32 v255, v82, v83
	global_store_dwordx4 v226, v[252:255], s[8:9] offset:256
	v_mul_f32_e32 v157, v77, v77
	v_mul_f32_e32 v158, v79, v79
	v_mul_f32_e32 v159, v73, v73
	v_mul_f32_e32 v153, v75, v75
	v_fmac_f32_e32 v157, v76, v76
	v_fmac_f32_e32 v158, v78, v78
	v_fmac_f32_e32 v159, v72, v72
	v_fmac_f32_e32 v153, v74, v74
	v_add_f32_e32 v157, v157, v158
	v_add_f32_e32 v157, v159, v157
	v_add_f32_e32 v235, v153, v157
	v_cvt_pk_bf16_f32 v248, v76, v77
	v_cvt_pk_bf16_f32 v249, v78, v79
	v_cvt_pk_bf16_f32 v250, v72, v73
	v_cvt_pk_bf16_f32 v251, v74, v75
	global_store_dwordx4 v227, v[248:251], s[8:9]
	v_mul_f32_e32 v157, v69, v69
	v_mul_f32_e32 v158, v71, v71
	v_mul_f32_e32 v159, v65, v65
	v_mul_f32_e32 v153, v67, v67
	v_fmac_f32_e32 v157, v68, v68
	v_fmac_f32_e32 v158, v70, v70
	v_fmac_f32_e32 v159, v64, v64
	v_fmac_f32_e32 v153, v66, v66
	v_add_f32_e32 v157, v157, v158
	v_add_f32_e32 v157, v159, v157
	v_add_f32_e32 v157, v153, v157
	v_add_f32_e32 v235, v235, v157
	v_cvt_pk_bf16_f32 v252, v68, v69
	v_cvt_pk_bf16_f32 v253, v70, v71
	v_cvt_pk_bf16_f32 v254, v64, v65
	v_cvt_pk_bf16_f32 v255, v66, v67
	global_store_dwordx4 v227, v[252:255], s[8:9] offset:256
	v_mul_f32_e32 v157, v61, v61
	v_mul_f32_e32 v158, v63, v63
	v_mul_f32_e32 v159, v57, v57
	v_mul_f32_e32 v153, v59, v59
	v_fmac_f32_e32 v157, v60, v60
	v_fmac_f32_e32 v158, v62, v62
	v_fmac_f32_e32 v159, v56, v56
	v_fmac_f32_e32 v153, v58, v58
	v_add_f32_e32 v157, v157, v158
	v_add_f32_e32 v157, v159, v157
	v_add_f32_e32 v236, v153, v157
	v_cvt_pk_bf16_f32 v248, v60, v61
	v_cvt_pk_bf16_f32 v249, v62, v63
	v_cvt_pk_bf16_f32 v250, v56, v57
	v_cvt_pk_bf16_f32 v251, v58, v59
	global_store_dwordx4 v228, v[248:251], s[8:9]
	v_mul_f32_e32 v157, v53, v53
	v_mul_f32_e32 v158, v55, v55
	v_mul_f32_e32 v159, v49, v49
	v_mul_f32_e32 v153, v51, v51
	v_fmac_f32_e32 v157, v52, v52
	v_fmac_f32_e32 v158, v54, v54
	v_fmac_f32_e32 v159, v48, v48
	v_fmac_f32_e32 v153, v50, v50
	v_add_f32_e32 v157, v157, v158
	v_add_f32_e32 v157, v159, v157
	v_add_f32_e32 v157, v153, v157
	v_add_f32_e32 v236, v236, v157
	v_cvt_pk_bf16_f32 v252, v52, v53
	v_cvt_pk_bf16_f32 v253, v54, v55
	v_cvt_pk_bf16_f32 v254, v48, v49
	v_cvt_pk_bf16_f32 v255, v50, v51
	global_store_dwordx4 v228, v[252:255], s[8:9] offset:256
	v_mul_f32_e32 v157, v45, v45
	v_mul_f32_e32 v158, v47, v47
	v_mul_f32_e32 v159, v41, v41
	v_mul_f32_e32 v153, v43, v43
	v_fmac_f32_e32 v157, v44, v44
	v_fmac_f32_e32 v158, v46, v46
	v_fmac_f32_e32 v159, v40, v40
	v_fmac_f32_e32 v153, v42, v42
	v_add_f32_e32 v157, v157, v158
	v_add_f32_e32 v157, v159, v157
	v_add_f32_e32 v237, v153, v157
	v_cvt_pk_bf16_f32 v248, v44, v45
	v_cvt_pk_bf16_f32 v249, v46, v47
	v_cvt_pk_bf16_f32 v250, v40, v41
	v_cvt_pk_bf16_f32 v251, v42, v43
	global_store_dwordx4 v229, v[248:251], s[8:9]
	v_mul_f32_e32 v157, v37, v37
	v_mul_f32_e32 v158, v39, v39
	v_mul_f32_e32 v159, v33, v33
	v_mul_f32_e32 v153, v35, v35
	v_fmac_f32_e32 v157, v36, v36
	v_fmac_f32_e32 v158, v38, v38
	v_fmac_f32_e32 v159, v32, v32
	v_fmac_f32_e32 v153, v34, v34
	v_add_f32_e32 v157, v157, v158
	v_add_f32_e32 v157, v159, v157
	v_add_f32_e32 v157, v153, v157
	v_add_f32_e32 v237, v237, v157
	v_cvt_pk_bf16_f32 v252, v36, v37
	v_cvt_pk_bf16_f32 v253, v38, v39
	v_cvt_pk_bf16_f32 v254, v32, v33
	v_cvt_pk_bf16_f32 v255, v34, v35
	global_store_dwordx4 v229, v[252:255], s[8:9] offset:256
	v_mul_f32_e32 v157, v29, v29
	v_mul_f32_e32 v158, v31, v31
	v_mul_f32_e32 v159, v25, v25
	v_mul_f32_e32 v153, v27, v27
	v_fmac_f32_e32 v157, v28, v28
	v_fmac_f32_e32 v158, v30, v30
	v_fmac_f32_e32 v159, v24, v24
	v_fmac_f32_e32 v153, v26, v26
	v_add_f32_e32 v157, v157, v158
	v_add_f32_e32 v157, v159, v157
	v_add_f32_e32 v238, v153, v157
	v_cvt_pk_bf16_f32 v248, v28, v29
	v_cvt_pk_bf16_f32 v249, v30, v31
	v_cvt_pk_bf16_f32 v250, v24, v25
	v_cvt_pk_bf16_f32 v251, v26, v27
	global_store_dwordx4 v230, v[248:251], s[8:9]
	v_mul_f32_e32 v157, v21, v21
	v_mul_f32_e32 v158, v23, v23
	v_mul_f32_e32 v159, v17, v17
	v_mul_f32_e32 v153, v19, v19
	v_fmac_f32_e32 v157, v20, v20
	v_fmac_f32_e32 v158, v22, v22
	v_fmac_f32_e32 v159, v16, v16
	v_fmac_f32_e32 v153, v18, v18
	v_add_f32_e32 v157, v157, v158
	v_add_f32_e32 v157, v159, v157
	v_add_f32_e32 v157, v153, v157
	v_add_f32_e32 v238, v238, v157
	v_cvt_pk_bf16_f32 v252, v20, v21
	v_cvt_pk_bf16_f32 v253, v22, v23
	v_cvt_pk_bf16_f32 v254, v16, v17
	v_cvt_pk_bf16_f32 v255, v18, v19
	global_store_dwordx4 v230, v[252:255], s[8:9] offset:256
	v_mul_f32_e32 v157, v13, v13
	v_mul_f32_e32 v158, v15, v15
	v_mul_f32_e32 v159, v9, v9
	v_mul_f32_e32 v153, v11, v11
	v_fmac_f32_e32 v157, v12, v12
	v_fmac_f32_e32 v158, v14, v14
	v_fmac_f32_e32 v159, v8, v8
	v_fmac_f32_e32 v153, v10, v10
	v_add_f32_e32 v157, v157, v158
	v_add_f32_e32 v157, v159, v157
	v_add_f32_e32 v239, v153, v157
	v_cvt_pk_bf16_f32 v248, v12, v13
	v_cvt_pk_bf16_f32 v249, v14, v15
	v_cvt_pk_bf16_f32 v250, v8, v9
	v_cvt_pk_bf16_f32 v251, v10, v11
	global_store_dwordx4 v231, v[248:251], s[8:9]
	v_mul_f32_e32 v157, v5, v5
	v_mul_f32_e32 v158, v7, v7
	v_mul_f32_e32 v159, v1, v1
	v_mul_f32_e32 v153, v3, v3
	v_fmac_f32_e32 v157, v4, v4
	v_fmac_f32_e32 v158, v6, v6
	v_fmac_f32_e32 v159, v0, v0
	v_fmac_f32_e32 v153, v2, v2
	v_add_f32_e32 v157, v157, v158
	v_add_f32_e32 v157, v159, v157
	v_add_f32_e32 v157, v153, v157
	v_add_f32_e32 v239, v239, v157
	v_cvt_pk_bf16_f32 v252, v4, v5
	v_cvt_pk_bf16_f32 v253, v6, v7
	v_cvt_pk_bf16_f32 v254, v0, v1
	v_cvt_pk_bf16_f32 v255, v2, v3
	global_store_dwordx4 v231, v[252:255], s[8:9] offset:256
	v_and_b32_e32 v145, 63, v154
	v_xor_b32_e32 v153, 16, v145
	v_xor_b32_e32 v145, 32, v145
	v_lshlrev_b32_e32 v153, 2, v153
	v_lshlrev_b32_e32 v145, 2, v145
	ds_bpermute_b32 v160, v153, v232
	ds_bpermute_b32 v161, v153, v233
	ds_bpermute_b32 v162, v153, v234
	ds_bpermute_b32 v163, v153, v235
	ds_bpermute_b32 v164, v153, v236
	ds_bpermute_b32 v165, v153, v237
	ds_bpermute_b32 v166, v153, v238
	ds_bpermute_b32 v167, v153, v239
	s_waitcnt lgkmcnt(0)
	v_add_f32_e32 v232, v232, v160
	v_add_f32_e32 v233, v233, v161
	v_add_f32_e32 v234, v234, v162
	v_add_f32_e32 v235, v235, v163
	v_add_f32_e32 v236, v236, v164
	v_add_f32_e32 v237, v237, v165
	v_add_f32_e32 v238, v238, v166
	v_add_f32_e32 v239, v239, v167
	ds_bpermute_b32 v160, v145, v232
	ds_bpermute_b32 v161, v145, v233
	ds_bpermute_b32 v162, v145, v234
	ds_bpermute_b32 v163, v145, v235
	ds_bpermute_b32 v164, v145, v236
	ds_bpermute_b32 v165, v145, v237
	ds_bpermute_b32 v166, v145, v238
	ds_bpermute_b32 v167, v145, v239
	v_cmp_eq_u32_e32 vcc, 0, v156
	s_waitcnt lgkmcnt(0)
	v_add_f32_e32 v232, v232, v160
	v_add_f32_e32 v233, v233, v161
	v_add_f32_e32 v234, v234, v162
	v_add_f32_e32 v235, v235, v163
	v_add_f32_e32 v236, v236, v164
	v_add_f32_e32 v237, v237, v165
	v_add_f32_e32 v238, v238, v166
	v_add_f32_e32 v239, v239, v167
	s_and_saveexec_b64 s[94:95], vcc
	global_store_dword v147, v232, s[10:11]
	global_store_dword v147, v233, s[10:11] offset:1024
	global_store_dword v147, v234, s[10:11] offset:2048
	global_store_dword v147, v235, s[10:11] offset:3072
	v_add_u32_e32 v172, 0x2000, v147
	global_store_dword v172, v236, s[10:11]
	v_add_u32_e32 v173, 0x2400, v147
	global_store_dword v173, v237, s[10:11]
	v_add_u32_e32 v174, 0x2800, v147
	global_store_dword v174, v238, s[10:11]
	v_add_u32_e32 v175, 0x2c00, v147
	global_store_dword v175, v239, s[10:11]
	s_or_b64 exec, exec, s[94:95]
	s_and_b64 vcc, exec, s[4:5]
	s_mov_b64 s[4:5], -1
	s_cbranch_vccnz .LBB0_1519
	s_andn2_b64 vcc, exec, s[12:13]
	s_cbranch_vccnz .LBB0_1518
	s_barrier
	s_branch .LBB0_1518
